# scan chunk derive: counted vmcnt waits leave the previous chunk's two result stores outstanding instead of draining them (bonus store made unconditional per half so the count is uniform)
# speedup vs baseline: 1.0042x; 1.0042x over previous
.LBB0_977:
	s_or_b64 exec, exec, s[24:25]
	v_lshlrev_b64 v[30:31], 1, v[26:27]
	v_lshl_add_u64 v[62:63], s[44:45], 0, v[30:31]
	v_lshl_add_u64 v[64:65], v[26:27], 2, s[46:47]
	v_lshl_add_u64 v[26:27], v[158:159], 1, v[62:63]
	v_lshl_add_u64 v[28:29], v[158:159], 2, v[64:65]
	global_load_dwordx2 v[70:71], v[26:27], off
	s_nop 0
	global_load_dwordx4 v[26:29], v[28:29], off
	global_load_dword v200, v[62:63], off
	global_load_dword v201, v[62:63], off
	s_ashr_i32 s23, s22, 31
	s_and_b32 s24, s72, 1
	s_lshl_b64 s[22:23], s[22:23], 1
	s_add_u32 s21, s68, s22
	s_addc_u32 s23, s69, s23
	s_lshl_b32 s22, s24, 6
	s_add_u32 s22, s21, s22
	s_addc_u32 s23, s23, 0
	s_ashr_i32 s21, s20, 31
	s_lshl_b64 s[20:21], s[20:21], 2
	s_add_u32 s20, s70, s20
	s_addc_u32 s21, s71, s21
	v_mov_b32_e32 v163, v0
	s_cmp_eq_u32 s24, 0
	v_lshl_add_u64 v[66:67], s[22:23], 0, v[162:163]
	s_cselect_b64 s[22:23], -1, 0
	s_lshl_b32 s24, s24, 7
	v_lshl_add_u64 v[68:69], s[38:39], 0, v[30:31]
	s_mov_b32 s48, 0
	s_mov_b64 s[22:23], s[18:19]
	v_add_u32_e32 v82, s24, v182
	v_add_u32_e32 v83, s24, v185
	v_mov_b64_e32 v[72:73], v[0:1]
	v_mov_b64_e32 v[74:75], v[0:1]
	v_mov_b64_e32 v[76:77], v[0:1]
	v_mov_b64_e32 v[78:79], v[0:1]
	s_branch .LBB0_979

.LBB0_979:
	s_waitcnt vmcnt(6)
	v_lshlrev_b32_e32 v30, 16, v50
	v_and_b32_e32 v31, 0xffff0000, v50
	v_lshlrev_b32_e32 v32, 16, v51
	v_and_b32_e32 v33, 0xffff0000, v51
	v_lshlrev_b32_e32 v1, 16, v56
	v_and_b32_e32 v34, 0xffff0000, v56
	v_lshlrev_b32_e32 v46, 16, v57
	v_and_b32_e32 v35, 0xffff0000, v57
	s_waitcnt vmcnt(5)
	v_lshlrev_b32_e32 v36, 16, v52
	v_and_b32_e32 v37, 0xffff0000, v52
	v_lshlrev_b32_e32 v38, 16, v53
	v_and_b32_e32 v39, 0xffff0000, v53
	v_lshlrev_b32_e32 v47, 16, v58
	v_and_b32_e32 v84, 0xffff0000, v58
	v_lshlrev_b32_e32 v85, 16, v59
	v_and_b32_e32 v86, 0xffff0000, v59
	v_sub_f32_e32 v45, v34, v31
	v_sub_f32_e32 v44, v1, v30
	v_sub_f32_e32 v35, v35, v33
	v_sub_f32_e32 v34, v46, v32
	v_pk_fma_f32 v[34:35], v[4:5], v[34:35], v[32:33]
	v_pk_fma_f32 v[32:33], v[2:3], v[44:45], v[30:31]
	v_sub_f32_e32 v31, v84, v37
	v_sub_f32_e32 v30, v47, v36
	v_sub_f32_e32 v45, v86, v39
	v_sub_f32_e32 v44, v85, v38
	s_waitcnt vmcnt(4)
	v_lshlrev_b32_e32 v40, 16, v54
	v_and_b32_e32 v41, 0xffff0000, v54
	v_lshlrev_b32_e32 v42, 16, v55
	v_and_b32_e32 v43, 0xffff0000, v55
	v_lshlrev_b32_e32 v87, 16, v60
	v_and_b32_e32 v88, 0xffff0000, v60
	v_lshlrev_b32_e32 v89, 16, v61
	v_and_b32_e32 v90, 0xffff0000, v61
	v_pk_fma_f32 v[44:45], v[8:9], v[44:45], v[38:39]
	v_pk_fma_f32 v[30:31], v[6:7], v[30:31], v[36:37]
	v_sub_f32_e32 v37, v88, v41
	v_sub_f32_e32 v36, v87, v40
	v_sub_f32_e32 v39, v90, v43
	v_sub_f32_e32 v38, v89, v42
	v_pk_mul_f32 v[84:85], v[14:15], v[30:31]
	v_pk_mul_f32 v[86:87], v[16:17], v[44:45]
	v_pk_fma_f32 v[38:39], v[12:13], v[38:39], v[42:43]
	v_pk_fma_f32 v[36:37], v[10:11], v[36:37], v[40:41]
	v_pk_mul_f32 v[40:41], v[86:87], v[86:87]
	v_pk_mul_f32 v[42:43], v[84:85], v[84:85]
	s_waitcnt vmcnt(3)
	v_lshlrev_b32_e32 v48, 16, v70
	v_pk_mov_b32 v[46:47], v[42:43], v[40:41] op_sel:[1,0]
	v_mov_b32_e32 v43, v41
	v_pk_add_f32 v[40:41], v[46:47], v[42:43]
	v_and_b32_e32 v49, 0xffff0000, v70
	v_lshlrev_b32_e32 v80, 16, v71
	v_and_b32_e32 v81, 0xffff0000, v71
	v_add_f32_e32 v1, v40, v41
	v_pk_add_f32 v[40:41], v[80:81], -1.0 op_sel_hi:[1,0]
	v_pk_add_f32 v[42:43], v[48:49], -1.0 op_sel_hi:[1,0]
	v_add_f32_dpp v1, v1, v1 quad_perm:[1,0,3,2] row_mask:0xf bank_mask:0xf bound_ctrl:1
	v_pk_fma_f32 v[46:47], v[18:19], v[42:43], 1.0 op_sel_hi:[1,1,0]
	v_pk_fma_f32 v[40:41], v[20:21], v[40:41], 1.0 op_sel_hi:[1,1,0]
	v_add_f32_dpp v1, v1, v1 quad_perm:[2,3,0,1] row_mask:0xf bank_mask:0xf bound_ctrl:1
	v_pk_mul_f32 v[42:43], v[44:45], v[40:41]
	v_pk_mul_f32 v[40:41], v[30:31], v[46:47]
	v_add_f32_dpp v1, v1, v1 row_half_mirror row_mask:0xf bank_mask:0xf bound_ctrl:1
	v_pk_mul_f32 v[30:31], v[32:33], v[40:41]
	v_pk_mul_f32 v[44:45], v[34:35], v[42:43]
	v_add_f32_dpp v1, v1, v1 row_ror:8 row_mask:0xf bank_mask:0xf bound_ctrl:1
	v_max_f32_e32 v1, 0x179abe15, v1
	v_pk_mul_f32 v[44:45], v[24:25], v[44:45]
	v_pk_mul_f32 v[30:31], v[22:23], v[30:31]
	v_rsq_f32_e32 v88, v1
	v_add_f32_e32 v1, v30, v31
	v_add_f32_e32 v30, v44, v45
	s_waitcnt vmcnt(2)
	v_exp_f32_e32 v44, v26
	v_exp_f32_e32 v45, v27
	v_exp_f32_e32 v46, v28
	v_exp_f32_e32 v47, v29
	v_add_f32_e32 v1, v1, v30
	ds_write_b128 v155, v[44:47]
	s_nop 0
	v_add_f32_dpp v1, v1, v1 quad_perm:[1,0,3,2] row_mask:0xf bank_mask:0xf bound_ctrl:1
	v_pk_mul_f32 v[46:47], v[86:87], v[88:89] op_sel_hi:[1,0] neg_lo:[0,1] neg_hi:[0,1]
	v_pk_mul_f32 v[44:45], v[84:85], v[88:89] op_sel_hi:[1,0] neg_lo:[0,1] neg_hi:[0,1]
	v_add_f32_dpp v1, v1, v1 quad_perm:[2,3,0,1] row_mask:0xf bank_mask:0xf bound_ctrl:1
	ds_write_b128 v155, v[44:47] offset:8192
	v_pk_mul_f32 v[46:47], v[46:47], v[80:81] neg_lo:[1,0] neg_hi:[1,0]
	v_add_f32_dpp v1, v1, v1 row_half_mirror row_mask:0xf bank_mask:0xf bound_ctrl:1
	v_pk_mul_f32 v[44:45], v[44:45], v[48:49] neg_lo:[1,0] neg_hi:[1,0]
	ds_write_b128 v155, v[44:47] offset:16384
	ds_write_b128 v155, v[40:43] offset:24576
	ds_write_b128 v155, v[32:35] offset:32768
	ds_write_b128 v155, v[36:39] offset:40960
	v_mov_b32_dpp v30, v1 row_ror:8 row_mask:0xf bank_mask:0xf bound_ctrl:1
	s_and_saveexec_b64 s[24:25], s[14:15]
	v_add_f32_e32 v1, v1, v30
	s_bitcmp1_b32 s48, 0
	s_cselect_b32 s100, 0x10100, 0
	v_add_u32_e32 v111, s100, v160
	ds_write_b32 v111, v1 offset:49152
	s_or_b64 exec, exec, s[24:25]
	s_add_i32 s49, s48, 1
	s_cmpk_eq_i32 s48, 0xff
	s_waitcnt lgkmcnt(0)
	s_barrier
	s_cbranch_scc1 .LBB0_985
	v_lshl_add_u32 v26, s49, 5, v154
	v_mad_i64_i32 v[28:29], s[24:25], v26, s59, v[68:69]
	v_add_co_u32_e32 v30, vcc, 0x1000, v28
	v_mov_b32_e32 v1, v0
	s_nop 0
	v_addc_co_u32_e32 v31, vcc, 0, v29, vcc
	global_load_dwordx2 v[50:51], v[28:29], off offset:3072
	global_load_dwordx2 v[52:53], v[30:31], off
	global_load_dwordx2 v[54:55], v[30:31], off offset:1024
	v_cmp_lt_i32_e32 vcc, 0, v26
	v_mov_b64_e32 v[60:61], v[0:1]
	v_mov_b64_e32 v[58:59], v[0:1]
	v_mov_b64_e32 v[56:57], v[0:1]
	s_and_saveexec_b64 s[24:25], vcc
	s_cbranch_execz .LBB0_984
	global_load_dwordx2 v[56:57], v[28:29], off offset:-3616
	global_load_dwordx2 v[58:59], v[28:29], off offset:-2592
	global_load_dwordx2 v[60:61], v[28:29], off offset:-1568

.LBB0_3078:
	s_or_b64 exec, exec, s[30:31]
	v_lshlrev_b64 v[30:31], 1, v[26:27]
	v_lshl_add_u64 v[62:63], s[48:49], 0, v[30:31]
	v_lshl_add_u64 v[64:65], v[26:27], 2, s[50:51]
	v_lshl_add_u64 v[26:27], v[158:159], 1, v[62:63]
	v_lshl_add_u64 v[28:29], v[158:159], 2, v[64:65]
	global_load_dwordx2 v[70:71], v[26:27], off
	s_nop 0
	global_load_dwordx4 v[26:29], v[28:29], off
	global_load_dword v200, v[62:63], off
	global_load_dword v201, v[62:63], off
	s_ashr_i32 s29, s28, 31
	s_and_b32 s6, s0, 1
	s_lshl_b64 s[0:1], s[28:29], 1
	s_add_u32 s0, s81, s0
	s_addc_u32 s1, s82, s1
	s_lshl_b32 s4, s6, 6
	s_add_u32 s0, s0, s4
	s_addc_u32 s1, s1, 0
	v_mov_b32_e32 v163, v0
	s_ashr_i32 s27, s26, 31
	v_lshl_add_u64 v[66:67], s[0:1], 0, v[162:163]
	s_lshl_b64 s[0:1], s[26:27], 2
	s_add_u32 s26, s83, s0
	s_addc_u32 s27, s84, s1
	s_cmp_eq_u32 s6, 0
	s_cselect_b64 s[4:5], -1, 0
	s_lshl_b32 s1, s6, 7
	v_lshl_add_u64 v[68:69], s[46:47], 0, v[30:31]
	s_mov_b32 s0, 0
	s_mov_b64 s[28:29], s[24:25]
	v_add_u32_e32 v82, s1, v182
	v_add_u32_e32 v83, s1, v185
	v_mov_b64_e32 v[72:73], v[0:1]
	v_mov_b64_e32 v[74:75], v[0:1]
	v_mov_b64_e32 v[76:77], v[0:1]
	v_mov_b64_e32 v[78:79], v[0:1]
	s_branch .LBB0_3080

.LBB0_3080:
	s_waitcnt vmcnt(6)
	v_lshlrev_b32_e32 v30, 16, v50
	v_and_b32_e32 v31, 0xffff0000, v50
	v_lshlrev_b32_e32 v32, 16, v51
	v_and_b32_e32 v33, 0xffff0000, v51
	v_lshlrev_b32_e32 v1, 16, v56
	v_and_b32_e32 v34, 0xffff0000, v56
	v_lshlrev_b32_e32 v46, 16, v57
	v_and_b32_e32 v35, 0xffff0000, v57
	s_waitcnt vmcnt(5)
	v_lshlrev_b32_e32 v36, 16, v52
	v_and_b32_e32 v37, 0xffff0000, v52
	v_lshlrev_b32_e32 v38, 16, v53
	v_and_b32_e32 v39, 0xffff0000, v53
	v_lshlrev_b32_e32 v47, 16, v58
	v_and_b32_e32 v84, 0xffff0000, v58
	v_lshlrev_b32_e32 v85, 16, v59
	v_and_b32_e32 v86, 0xffff0000, v59
	v_sub_f32_e32 v45, v34, v31
	v_sub_f32_e32 v44, v1, v30
	v_sub_f32_e32 v35, v35, v33
	v_sub_f32_e32 v34, v46, v32
	v_pk_fma_f32 v[34:35], v[4:5], v[34:35], v[32:33]
	v_pk_fma_f32 v[32:33], v[2:3], v[44:45], v[30:31]
	v_sub_f32_e32 v31, v84, v37
	v_sub_f32_e32 v30, v47, v36
	v_sub_f32_e32 v45, v86, v39
	v_sub_f32_e32 v44, v85, v38
	s_waitcnt vmcnt(4)
	v_lshlrev_b32_e32 v40, 16, v54
	v_and_b32_e32 v41, 0xffff0000, v54
	v_lshlrev_b32_e32 v42, 16, v55
	v_and_b32_e32 v43, 0xffff0000, v55
	v_lshlrev_b32_e32 v87, 16, v60
	v_and_b32_e32 v88, 0xffff0000, v60
	v_lshlrev_b32_e32 v89, 16, v61
	v_and_b32_e32 v90, 0xffff0000, v61
	v_pk_fma_f32 v[44:45], v[8:9], v[44:45], v[38:39]
	v_pk_fma_f32 v[30:31], v[6:7], v[30:31], v[36:37]
	v_sub_f32_e32 v37, v88, v41
	v_sub_f32_e32 v36, v87, v40
	v_sub_f32_e32 v39, v90, v43
	v_sub_f32_e32 v38, v89, v42
	v_pk_mul_f32 v[84:85], v[14:15], v[30:31]
	v_pk_mul_f32 v[86:87], v[16:17], v[44:45]
	v_pk_fma_f32 v[38:39], v[12:13], v[38:39], v[42:43]
	v_pk_fma_f32 v[36:37], v[10:11], v[36:37], v[40:41]
	v_pk_mul_f32 v[40:41], v[86:87], v[86:87]
	v_pk_mul_f32 v[42:43], v[84:85], v[84:85]
	s_waitcnt vmcnt(3)
	v_lshlrev_b32_e32 v48, 16, v70
	v_pk_mov_b32 v[46:47], v[42:43], v[40:41] op_sel:[1,0]
	v_mov_b32_e32 v43, v41
	v_pk_add_f32 v[40:41], v[46:47], v[42:43]
	v_and_b32_e32 v49, 0xffff0000, v70
	v_lshlrev_b32_e32 v80, 16, v71
	v_and_b32_e32 v81, 0xffff0000, v71
	v_add_f32_e32 v1, v40, v41
	v_pk_add_f32 v[40:41], v[80:81], -1.0 op_sel_hi:[1,0]
	v_pk_add_f32 v[42:43], v[48:49], -1.0 op_sel_hi:[1,0]
	v_add_f32_dpp v1, v1, v1 quad_perm:[1,0,3,2] row_mask:0xf bank_mask:0xf bound_ctrl:1
	v_pk_fma_f32 v[46:47], v[18:19], v[42:43], 1.0 op_sel_hi:[1,1,0]
	v_pk_fma_f32 v[40:41], v[20:21], v[40:41], 1.0 op_sel_hi:[1,1,0]
	v_add_f32_dpp v1, v1, v1 quad_perm:[2,3,0,1] row_mask:0xf bank_mask:0xf bound_ctrl:1
	v_pk_mul_f32 v[42:43], v[44:45], v[40:41]
	v_pk_mul_f32 v[40:41], v[30:31], v[46:47]
	v_add_f32_dpp v1, v1, v1 row_half_mirror row_mask:0xf bank_mask:0xf bound_ctrl:1
	v_pk_mul_f32 v[30:31], v[32:33], v[40:41]
	v_pk_mul_f32 v[44:45], v[34:35], v[42:43]
	v_add_f32_dpp v1, v1, v1 row_ror:8 row_mask:0xf bank_mask:0xf bound_ctrl:1
	v_max_f32_e32 v1, 0x179abe15, v1
	v_pk_mul_f32 v[44:45], v[24:25], v[44:45]
	v_pk_mul_f32 v[30:31], v[22:23], v[30:31]
	v_rsq_f32_e32 v88, v1
	v_add_f32_e32 v1, v30, v31
	v_add_f32_e32 v30, v44, v45
	s_waitcnt vmcnt(2)
	v_exp_f32_e32 v44, v26
	v_exp_f32_e32 v45, v27
	v_exp_f32_e32 v46, v28
	v_exp_f32_e32 v47, v29
	v_add_f32_e32 v1, v1, v30
	ds_write_b128 v155, v[44:47]
	s_nop 0
	v_add_f32_dpp v1, v1, v1 quad_perm:[1,0,3,2] row_mask:0xf bank_mask:0xf bound_ctrl:1
	v_pk_mul_f32 v[46:47], v[86:87], v[88:89] op_sel_hi:[1,0] neg_lo:[0,1] neg_hi:[0,1]
	v_pk_mul_f32 v[44:45], v[84:85], v[88:89] op_sel_hi:[1,0] neg_lo:[0,1] neg_hi:[0,1]
	v_add_f32_dpp v1, v1, v1 quad_perm:[2,3,0,1] row_mask:0xf bank_mask:0xf bound_ctrl:1
	ds_write_b128 v155, v[44:47] offset:8192
	v_pk_mul_f32 v[46:47], v[46:47], v[80:81] neg_lo:[1,0] neg_hi:[1,0]
	v_add_f32_dpp v1, v1, v1 row_half_mirror row_mask:0xf bank_mask:0xf bound_ctrl:1
	v_pk_mul_f32 v[44:45], v[44:45], v[48:49] neg_lo:[1,0] neg_hi:[1,0]
	ds_write_b128 v155, v[44:47] offset:16384
	ds_write_b128 v155, v[40:43] offset:24576
	ds_write_b128 v155, v[32:35] offset:32768
	ds_write_b128 v155, v[36:39] offset:40960
	v_mov_b32_dpp v30, v1 row_ror:8 row_mask:0xf bank_mask:0xf bound_ctrl:1
	s_and_saveexec_b64 s[30:31], s[20:21]
	v_add_f32_e32 v1, v1, v30
	s_bitcmp1_b32 s0, 0
	s_cselect_b32 s100, 0x10100, 0
	v_add_u32_e32 v111, s100, v160
	ds_write_b32 v111, v1 offset:49152
	s_or_b64 exec, exec, s[30:31]
	s_add_i32 s1, s0, 1
	s_cmpk_eq_i32 s0, 0xff
	s_waitcnt lgkmcnt(0)
	s_barrier
	s_cbranch_scc1 .LBB0_3086
	v_lshl_add_u32 v26, s1, 5, v154
	v_mad_i64_i32 v[28:29], s[4:5], v26, s72, v[68:69]
	v_add_co_u32_e32 v30, vcc, 0x1000, v28
	v_mov_b32_e32 v1, v0
	s_nop 0
	v_addc_co_u32_e32 v31, vcc, 0, v29, vcc
	global_load_dwordx2 v[50:51], v[28:29], off offset:3072
	global_load_dwordx2 v[52:53], v[30:31], off
	global_load_dwordx2 v[54:55], v[30:31], off offset:1024
	v_cmp_lt_i32_e32 vcc, 0, v26
	v_mov_b64_e32 v[60:61], v[0:1]
	v_mov_b64_e32 v[58:59], v[0:1]
	v_mov_b64_e32 v[56:57], v[0:1]
	s_and_saveexec_b64 s[30:31], vcc
	s_cbranch_execz .LBB0_3085
	global_load_dwordx2 v[56:57], v[28:29], off offset:-3616
	global_load_dwordx2 v[58:59], v[28:29], off offset:-2592
	global_load_dwordx2 v[60:61], v[28:29], off offset:-1568
